# one in-loop copy slot per K-iteration in both the gate/up and the down-projection GEMM loops (37.5 percent of the plain-copy units), no epilogue copies
# baseline (speedup 1.0000x reference)
.LBB0_1208:
	s_add_i32 s95, s95, 1
	s_mul_i32 s8, s95, s40
	s_mov_b32 s82, s40
	s_cmpk_gt_i32 s8, 0x38ff
	s_cbranch_scc1 .LBB0_1379
.LBB0_1209:
	v_readlane_b32 s10, v240, 0
	s_add_i32 s12, s8, s10
	s_lshl_b32 s8, s95, 8
	s_add_i32 s8, s8, s15
	s_ashr_i32 s9, s8, 7
	v_readlane_b32 s11, v240, 1
	s_mul_hi_i32 s10, s9, 0x55555556
	s_lshr_b32 s11, s10, 31
	s_add_i32 s10, s10, s11
	s_mul_i32 s11, s14, 3
	s_add_i32 s11, s10, s11
	s_mul_i32 s10, s10, 3
	s_mul_i32 s11, s11, 3
	s_sub_i32 s10, s9, s10
	s_add_i32 s11, s11, s10
	s_mul_hi_i32 s10, s8, 0x30c30c31
	s_lshr_b32 s16, s10, 31
	s_ashr_i32 s10, s10, 4
	s_add_i32 s10, s10, s16
	s_lshl_b32 s16, s10, 3
	s_or_b32 s16, s16, s14
	s_mulk_i32 s10, 0x54
	s_mulk_i32 s16, 0x54
	s_sub_i32 s10, s8, s10
	s_add_i32 s13, s12, 0x2a00
	s_add_i32 s96, s12, 0xffffdf00
	s_add_i32 s16, s16, s10
	s_cmp_lt_u32 s9, 12
	s_cselect_b32 s10, s19, s2
	s_add_i32 s10, s10, s9
	s_cmp_lt_i32 s9, 9
	s_cselect_b32 s9, s11, s10
	s_lshl_b32 s9, s9, 7
	s_add_i32 s17, s9, s35
	s_cmpk_lt_i32 s8, 0x540
	s_cselect_b32 s10, s16, -1
	s_and_b64 s[8:9], s[58:59], exec
	s_cselect_b32 s16, s12, s10
	s_cmpk_gt_i32 s12, 0x29ff
	s_cselect_b64 s[8:9], -1, 0
	s_and_b64 s[10:11], s[8:9], exec
	s_cselect_b32 s97, -1, s16
	s_or_b64 s[8:9], s[8:9], s[58:59]
	s_cmpk_lt_u32 s96, 0x1800
	s_cselect_b64 s[10:11], -1, 0
	s_and_b64 s[74:75], s[8:9], s[10:11]
	s_and_b64 s[8:9], s[58:59], exec
	s_cselect_b32 s8, s13, s17
	s_cmpk_lt_i32 s12, 0x3800
	s_mov_b32 s40, s82
	s_cselect_b32 s52, s8, -1
	s_mov_b64 s[76:77], -1
	s_mov_b32 s10, s57
	s_branch .LBB0_1212

.LBB0_1723:
	s_and_b64 vcc, exec, s[4:5]
	s_cbranch_vccnz .LBB0_1763
	s_lshr_b32 s32, s69, 7
	s_lshl_b32 s32, s32, 3
	s_load_dwordx2 s[96:97], s[0:1], s32 offset:0x20
	s_load_dwordx2 s[72:73], s[0:1], 0xa0
	s_and_b32 s100, s69, 0x7f
	s_mul_i32 s100, s100, 0x300000
	s_mov_b32 s101, 0x1ee80000
	s_cmp_lt_u32 s69, 0x80
	s_cselect_b32 s101, 0x6e80000, s101
	v_and_b32_e32 v238, 63, v164
	v_lshlrev_b32_e32 v238, 4, v238
	v_readfirstlane_b32 s76, v164
	s_waitcnt lgkmcnt(0)
	s_add_u32 s96, s96, s100
	s_addc_u32 s97, s97, 0
	s_add_u32 s96, s96, 0x3000
	s_addc_u32 s97, s97, 0
	s_and_b32 s97, s97, 0xffff
	s_mov_b32 s98, 0x300000
	s_mov_b32 s99, 0x20000
	s_add_u32 s72, s72, s101
	s_addc_u32 s73, s73, 0
	s_add_u32 s72, s72, s100
	s_addc_u32 s73, s73, 0
	s_and_b32 s73, s73, 0xffff
	s_mov_b32 s74, 0x300000
	s_mov_b32 s75, 0x20000
	s_lshr_b32 s76, s76, 6
	s_mul_i32 s101, s76, 0x4800
	s_mul_i32 s100, s76, 1
	s_lshr_b32 s32, s76, 1
	s_mul_i32 s32, s32, 1
	s_add_u32 s100, s100, s32
	s_mul_i32 s100, s100, 0x3000
	s_add_u32 s101, s101, s100
	s_add_u32 s101, s101, 0x90000
	s_add_u32 s100, s101, 0x400
	s_and_b32 s32, s76, 1
	s_mul_i32 s32, s32, 6
	s_add_u32 s32, s32, 1
	s_mov_b32 s76, 18
	buffer_load_dwordx4 v[234:237], v238, s[96:99], s101 offen nt
	v_ashrrev_i32_e32 v1, 31, v164
	v_lshrrev_b32_e32 v1, 26, v1
	v_add_u32_e32 v1, v164, v1
	v_ashrrev_i32_e32 v8, 6, v1
	v_bfe_i32 v1, v164, 27, 1
	v_lshlrev_b32_e32 v0, 4, v164
	v_lshrrev_b32_e32 v1, 22, v1
	v_add_u32_e32 v1, v0, v1
	v_and_b32_e32 v1, 0xfffffc00, v1
	v_sub_u32_e32 v1, v0, v1
	v_lshrrev_b32_e32 v2, 4, v1
	v_bitop3_b32 v1, v2, v1, 32 bitop3:0x6c
	v_ashrrev_i32_e32 v3, 31, v1
	v_lshrrev_b32_e32 v3, 26, v3
	v_lshlrev_b32_e32 v2, 3, v8
	v_add_u32_e32 v3, v1, v3
	v_and_b32_e32 v2, -16, v2
	v_ashrrev_i32_e32 v10, 6, v3
	v_and_b32_e32 v3, 0xc0, v3
	v_add_u32_e32 v2, v10, v2
	v_lshlrev_b32_e32 v4, 5, v8
	v_sub_u32_e32 v1, v1, v3
	v_mov_b32_e32 v3, 1
	v_and_b32_e32 v9, 32, v4
	v_ashrrev_i16_sdwa v1, v3, sext(v1) dst_sel:DWORD dst_unused:UNUSED_PAD src0_sel:DWORD src1_sel:BYTE_0
	v_lshlrev_b32_e32 v4, 1, v2
	v_lshrrev_b32_e32 v5, 2, v2
	v_and_b32_e32 v6, 3, v10
	s_mov_b32 s3, 0xffffe0
	v_bfe_i32 v11, v1, 0, 16
	v_and_b32_e32 v4, 24, v4
	v_and_b32_e32 v5, 4, v5
	v_and_or_b32 v6, v2, s3, v6
	s_movk_i32 s6, 0xb00
	v_add_u32_e32 v1, v9, v11
	v_or3_b32 v4, v6, v5, v4
	v_mul_lo_u32 v2, v2, s6
	v_add_lshl_u32 v130, v1, v2, 1
	v_mul_u32_u24_e32 v2, 0xb00, v4
	v_add_u32_e32 v0, 0x2000, v0
	v_add_lshl_u32 v132, v2, v1, 1
	v_ashrrev_i32_e32 v1, 31, v0
	v_lshrrev_b32_e32 v1, 22, v1
	v_add_u32_e32 v1, v0, v1
	v_ashrrev_i32_e32 v12, 10, v1
	v_mul_i32_i24_e32 v1, 0x400, v12
	v_sub_u32_e32 v0, v0, v1
	v_lshrrev_b32_e32 v1, 4, v0
	v_bitop3_b32 v0, v1, v0, 32 bitop3:0x6c
	v_ashrrev_i32_e32 v2, 31, v0
	v_lshrrev_b32_e32 v2, 26, v2
	v_lshlrev_b32_e32 v1, 3, v12
	v_add_u32_e32 v2, v0, v2
	s_ashr_i32 s4, s2, 6
	v_and_b32_e32 v1, -16, v1
	v_ashrrev_i32_e32 v13, 6, v2
	v_and_b32_e32 v2, 0xc0, v2
	v_add_u32_e32 v1, v13, v1
	v_lshlrev_b32_e32 v4, 5, v12
	v_sub_u32_e32 v0, v0, v2
	s_ashr_i32 s5, s2, 8
	s_lshl_b32 s15, s4, 10
	s_mul_i32 s11, s14, 0x160000
	v_and_b32_e32 v14, 32, v4
	v_ashrrev_i16_sdwa v0, v3, sext(v0) dst_sel:DWORD dst_unused:UNUSED_PAD src0_sel:DWORD src1_sel:BYTE_0
	v_lshlrev_b32_e32 v2, 1, v1
	v_lshrrev_b32_e32 v3, 2, v1
	v_and_b32_e32 v4, 3, v13
	s_mul_hi_i32 s10, s14, 0x160000
	s_add_u32 s54, s90, s11
	v_bfe_i32 v15, v0, 0, 16
	v_and_b32_e32 v2, 24, v2
	v_and_b32_e32 v3, 4, v3
	v_and_or_b32 v4, v1, s3, v4
	s_addc_u32 s55, s91, s10
	s_add_i32 s18, s15, 0
	v_add_u32_e32 v0, v14, v15
	v_or3_b32 v2, v4, v3, v2
	v_mul_lo_u32 v1, v1, s6
	s_add_i32 m0, s18, 0x10000
	v_add_lshl_u32 v134, v0, v1, 1
	v_mul_u32_u24_e32 v1, 0xb00, v2
	global_load_lds_dwordx4 v132, s[54:55]
	s_add_i32 m0, s18, 0x12000
	v_add_lshl_u32 v136, v1, v0, 1
	s_add_u32 s10, s54, 0xb0000
	global_load_lds_dwordx4 v136, s[54:55]
	s_addc_u32 s11, s55, 0
	s_add_i32 m0, s18, 0x14000
	s_mul_i32 s7, s67, 0x160000
	global_load_lds_dwordx4 v132, s[10:11]
	s_add_i32 m0, s18, 0x16000
	s_mul_hi_i32 s3, s67, 0x160000
	s_add_u32 s52, s8, s7
	s_addc_u32 s53, s9, s3
	s_add_i32 s19, s18, 0x2000
	global_load_lds_dwordx4 v136, s[10:11]
	s_mov_b32 m0, s18
	s_add_u32 s10, s52, 0xb0000
	global_load_lds_dwordx4 v130, s[52:53]
	s_mov_b32 m0, s19
	s_addc_u32 s11, s53, 0
	s_add_i32 s35, s18, 0x4000
	global_load_lds_dwordx4 v134, s[52:53]
	s_mov_b32 m0, s35
	s_add_i32 s43, s18, 0x6000
	global_load_lds_dwordx4 v130, s[10:11]
	s_mov_b32 m0, s43
	v_mov_b32_e32 v139, 0
	global_load_lds_dwordx4 v134, s[10:11]
	v_mov_b32_e32 v133, v139
	v_mov_b32_e32 v137, v139
	v_mov_b32_e32 v131, v139
	v_mov_b32_e32 v135, v139
	s_cmp_eq_u32 s5, 1
	s_mov_b32 s3, 0
	v_lshl_add_u64 v[6:7], s[54:55], 0, v[132:133]
	v_lshl_add_u64 v[4:5], s[54:55], 0, v[136:137]
	v_lshl_add_u64 v[0:1], s[52:53], 0, v[130:131]
	s_cselect_b64 s[10:11], -1, 0
	s_cmp_lg_u32 s5, 1
	v_lshl_add_u64 v[2:3], s[52:53], 0, v[134:135]
	s_cbranch_scc1 .LBB0_1726
	s_barrier

.LBB0_1735:
	ds_read_b128 v[162:165], v159
	ds_read_b128 v[166:169], v159 offset:1024
	ds_read_b128 v[170:173], v159 offset:2048
	ds_read_b128 v[174:177], v159 offset:3072
	ds_read_b128 v[178:181], v160
	ds_read_b128 v[182:185], v160 offset:1024
	ds_read_b128 v[186:189], v160 offset:2048
	ds_read_b128 v[190:193], v160 offset:3072
	s_add_i32 s68, s56, 2
	s_add_u32 s54, s52, 0x100
	s_addc_u32 s55, s53, 0
	s_cmp_eq_u32 s34, s56
	s_cselect_b32 s56, s48, s37
	s_cselect_b32 s59, s39, s55
	s_cselect_b32 s58, s38, s54
	s_cselect_b32 s57, s49, s42
	v_lshl_add_u64 v[146:147], s[52:53], 0, v[142:143]
	s_add_i32 m0, s18, 0xc000
	ds_read_b128 v[194:197], v161
	ds_read_b128 v[198:201], v161 offset:1024
	ds_read_b128 v[202:205], v161 offset:2048
	ds_read_b128 v[206:209], v161 offset:3072
	ds_read_b128 v[210:213], v161 offset:4096
	ds_read_b128 v[214:217], v161 offset:5120
	ds_read_b128 v[218:221], v161 offset:6144
	ds_read_b128 v[222:225], v161 offset:7168
	global_load_lds_dwordx4 v[146:147], off
	v_lshl_add_u64 v[146:147], s[52:53], 0, v[144:145]
	s_add_i32 m0, s18, 0xe000
	s_nop 0
	global_load_lds_dwordx4 v[146:147], off
	s_waitcnt vmcnt(9)
	s_waitcnt lgkmcnt(0)
	s_barrier
	s_setprio 1
	s_waitcnt lgkmcnt(0)
	v_mfma_f32_16x16x32_bf16 v[124:127], v[162:165], v[194:197], v[124:127]
	v_mfma_f32_16x16x32_bf16 v[120:123], v[170:173], v[194:197], v[120:123]
	v_mfma_f32_16x16x32_bf16 v[108:111], v[162:165], v[202:205], v[108:111]
	v_mfma_f32_16x16x32_bf16 v[104:107], v[170:173], v[202:205], v[104:107]
	v_mfma_f32_16x16x32_bf16 v[92:95], v[162:165], v[210:213], v[92:95]
	v_mfma_f32_16x16x32_bf16 v[88:91], v[170:173], v[210:213], v[88:91]
	v_mfma_f32_16x16x32_bf16 v[76:79], v[162:165], v[218:221], v[76:79]
	v_mfma_f32_16x16x32_bf16 v[72:75], v[170:173], v[218:221], v[72:75]
	v_mfma_f32_16x16x32_bf16 v[124:127], v[166:169], v[198:201], v[124:127]
	v_mfma_f32_16x16x32_bf16 v[120:123], v[174:177], v[198:201], v[120:123]
	v_mfma_f32_16x16x32_bf16 v[108:111], v[166:169], v[206:209], v[108:111]
	v_mfma_f32_16x16x32_bf16 v[104:107], v[174:177], v[206:209], v[104:107]
	v_mfma_f32_16x16x32_bf16 v[92:95], v[166:169], v[214:217], v[92:95]
	v_mfma_f32_16x16x32_bf16 v[88:91], v[174:177], v[214:217], v[88:91]
	v_mfma_f32_16x16x32_bf16 v[76:79], v[166:169], v[222:225], v[76:79]
	v_mfma_f32_16x16x32_bf16 v[72:75], v[174:177], v[222:225], v[72:75]
	s_setprio 0
	s_setprio 1
	v_mfma_f32_16x16x32_bf16 v[116:119], v[178:181], v[194:197], v[116:119]
	v_mfma_f32_16x16x32_bf16 v[112:115], v[186:189], v[194:197], v[112:115]
	v_mfma_f32_16x16x32_bf16 v[100:103], v[178:181], v[202:205], v[100:103]
	v_mfma_f32_16x16x32_bf16 v[96:99], v[186:189], v[202:205], v[96:99]
	v_mfma_f32_16x16x32_bf16 v[84:87], v[178:181], v[210:213], v[84:87]
	v_mfma_f32_16x16x32_bf16 v[80:83], v[186:189], v[210:213], v[80:83]
	v_mfma_f32_16x16x32_bf16 v[68:71], v[178:181], v[218:221], v[68:71]
	v_mfma_f32_16x16x32_bf16 v[64:67], v[186:189], v[218:221], v[64:67]
	v_mfma_f32_16x16x32_bf16 v[116:119], v[182:185], v[198:201], v[116:119]
	v_mfma_f32_16x16x32_bf16 v[112:115], v[190:193], v[198:201], v[112:115]
	v_mfma_f32_16x16x32_bf16 v[100:103], v[182:185], v[206:209], v[100:103]
	v_mfma_f32_16x16x32_bf16 v[96:99], v[190:193], v[206:209], v[96:99]
	v_mfma_f32_16x16x32_bf16 v[84:87], v[182:185], v[214:217], v[84:87]
	v_mfma_f32_16x16x32_bf16 v[80:83], v[190:193], v[214:217], v[80:83]
	v_mfma_f32_16x16x32_bf16 v[68:71], v[182:185], v[222:225], v[68:71]
	v_mfma_f32_16x16x32_bf16 v[64:67], v[190:193], v[222:225], v[64:67]
	s_setprio 0
	s_barrier
	s_add_i32 s52, s63, s15
	v_lshl_add_u64 v[146:147], s[56:57], 0, v[132:133]
	s_mov_b32 m0, s52
	ds_read_b128 v[194:197], v161 offset:16384
	ds_read_b128 v[198:201], v161 offset:17408
	ds_read_b128 v[202:205], v161 offset:18432
	ds_read_b128 v[206:209], v161 offset:19456
	ds_read_b128 v[210:213], v161 offset:20480
	ds_read_b128 v[214:217], v161 offset:21504
	ds_read_b128 v[218:221], v161 offset:22528
	ds_read_b128 v[222:225], v161 offset:23552
	global_load_lds_dwordx4 v[146:147], off
	s_add_i32 m0, s52, 0x2000
	s_add_u32 s52, s56, 0xb0000
	v_lshl_add_u64 v[226:227], s[56:57], 0, v[136:137]
	s_addc_u32 s53, s57, 0
	s_add_i32 s69, s64, s15
	global_load_lds_dwordx4 v[226:227], off
	v_lshl_add_u64 v[228:229], s[52:53], 0, v[132:133]
	s_mov_b32 m0, s69
	v_lshl_add_u64 v[230:231], s[58:59], 0, v[134:135]
	global_load_lds_dwordx4 v[228:229], off
	v_lshl_add_u64 v[228:229], s[52:53], 0, v[136:137]
	s_add_i32 m0, s69, 0x2000
	s_nop 0
	global_load_lds_dwordx4 v[228:229], off
	v_lshl_add_u64 v[228:229], s[58:59], 0, v[130:131]
	s_mov_b32 m0, s18
	s_nop 0
	global_load_lds_dwordx4 v[228:229], off
	s_mov_b32 m0, s19
	s_nop 0
	global_load_lds_dwordx4 v[230:231], off
	s_waitcnt vmcnt(8)
	s_waitcnt lgkmcnt(0)
	s_barrier
	s_setprio 1
	s_waitcnt lgkmcnt(0)
	v_mfma_f32_16x16x32_bf16 v[60:63], v[162:165], v[194:197], v[60:63]
	v_mfma_f32_16x16x32_bf16 v[56:59], v[170:173], v[194:197], v[56:59]
	v_mfma_f32_16x16x32_bf16 v[44:47], v[162:165], v[202:205], v[44:47]
	v_mfma_f32_16x16x32_bf16 v[40:43], v[170:173], v[202:205], v[40:43]
	v_mfma_f32_16x16x32_bf16 v[28:31], v[162:165], v[210:213], v[28:31]
	v_mfma_f32_16x16x32_bf16 v[24:27], v[170:173], v[210:213], v[24:27]
	v_mfma_f32_16x16x32_bf16 v[12:15], v[162:165], v[218:221], v[12:15]
	v_mfma_f32_16x16x32_bf16 v[8:11], v[170:173], v[218:221], v[8:11]
	v_mfma_f32_16x16x32_bf16 v[60:63], v[166:169], v[198:201], v[60:63]
	v_mfma_f32_16x16x32_bf16 v[56:59], v[174:177], v[198:201], v[56:59]
	v_mfma_f32_16x16x32_bf16 v[44:47], v[166:169], v[206:209], v[44:47]
	v_mfma_f32_16x16x32_bf16 v[40:43], v[174:177], v[206:209], v[40:43]
	v_mfma_f32_16x16x32_bf16 v[28:31], v[166:169], v[214:217], v[28:31]
	v_mfma_f32_16x16x32_bf16 v[24:27], v[174:177], v[214:217], v[24:27]
	v_mfma_f32_16x16x32_bf16 v[12:15], v[166:169], v[222:225], v[12:15]
	v_mfma_f32_16x16x32_bf16 v[8:11], v[174:177], v[222:225], v[8:11]
	s_setprio 0
	s_setprio 1
	v_mfma_f32_16x16x32_bf16 v[52:55], v[178:181], v[194:197], v[52:55]
	v_mfma_f32_16x16x32_bf16 v[48:51], v[186:189], v[194:197], v[48:51]
	v_mfma_f32_16x16x32_bf16 v[36:39], v[178:181], v[202:205], v[36:39]
	v_mfma_f32_16x16x32_bf16 v[32:35], v[186:189], v[202:205], v[32:35]
	v_mfma_f32_16x16x32_bf16 v[20:23], v[178:181], v[210:213], v[20:23]
	v_mfma_f32_16x16x32_bf16 v[16:19], v[186:189], v[210:213], v[16:19]
	v_mfma_f32_16x16x32_bf16 v[4:7], v[178:181], v[218:221], v[4:7]
	v_mfma_f32_16x16x32_bf16 v[0:3], v[186:189], v[218:221], v[0:3]
	v_mfma_f32_16x16x32_bf16 v[52:55], v[182:185], v[198:201], v[52:55]
	v_mfma_f32_16x16x32_bf16 v[48:51], v[190:193], v[198:201], v[48:51]
	v_mfma_f32_16x16x32_bf16 v[36:39], v[182:185], v[206:209], v[36:39]
	v_mfma_f32_16x16x32_bf16 v[32:35], v[190:193], v[206:209], v[32:35]
	v_mfma_f32_16x16x32_bf16 v[20:23], v[182:185], v[214:217], v[20:23]
	v_mfma_f32_16x16x32_bf16 v[16:19], v[190:193], v[214:217], v[16:19]
	v_mfma_f32_16x16x32_bf16 v[4:7], v[182:185], v[222:225], v[4:7]
	v_mfma_f32_16x16x32_bf16 v[0:3], v[190:193], v[222:225], v[0:3]
	s_setprio 0
	s_barrier
	buffer_store_dwordx4 v[234:237], v238, s[72:75], s101 offen nt
	s_add_i32 s69, 0, 0x18000
	v_add_u32_e32 v138, s69, v141
	s_add_i32 s70, 0, 0x1c000
	ds_read_b128 v[162:165], v138
	ds_read_b128 v[166:169], v138 offset:1024
	ds_read_b128 v[170:173], v138 offset:2048
	ds_read_b128 v[174:177], v138 offset:3072
	v_add_u32_e32 v138, s70, v141
	ds_read_b128 v[178:181], v138
	ds_read_b128 v[182:185], v138 offset:1024
	ds_read_b128 v[186:189], v138 offset:2048
	ds_read_b128 v[190:193], v138 offset:3072
	s_add_u32 s52, s58, 0xb0000
	s_addc_u32 s53, s59, 0
	s_mov_b32 m0, s35
	v_lshl_add_u64 v[232:233], s[52:53], 0, v[130:131]
	ds_read_b128 v[194:197], v161 offset:32768
	ds_read_b128 v[198:201], v161 offset:33792
	ds_read_b128 v[202:205], v161 offset:34816
	ds_read_b128 v[206:209], v161 offset:35840
	ds_read_b128 v[210:213], v161 offset:36864
	ds_read_b128 v[214:217], v161 offset:37888
	ds_read_b128 v[218:221], v161 offset:38912
	ds_read_b128 v[222:225], v161 offset:39936
	global_load_lds_dwordx4 v[232:233], off
	v_lshl_add_u64 v[232:233], s[52:53], 0, v[134:135]
	s_mov_b32 m0, s43
	s_nop 0
	global_load_lds_dwordx4 v[232:233], off
	buffer_load_dwordx4 v[234:237], v238, s[96:99], s100 offen nt
	s_waitcnt vmcnt(10)
	s_waitcnt lgkmcnt(0)
	s_barrier
	s_setprio 1
	s_waitcnt lgkmcnt(0)
	v_mfma_f32_16x16x32_bf16 v[124:127], v[162:165], v[194:197], v[124:127]
	v_mfma_f32_16x16x32_bf16 v[120:123], v[170:173], v[194:197], v[120:123]
	v_mfma_f32_16x16x32_bf16 v[108:111], v[162:165], v[202:205], v[108:111]
	v_mfma_f32_16x16x32_bf16 v[104:107], v[170:173], v[202:205], v[104:107]
	v_mfma_f32_16x16x32_bf16 v[92:95], v[162:165], v[210:213], v[92:95]
	v_mfma_f32_16x16x32_bf16 v[88:91], v[170:173], v[210:213], v[88:91]
	v_mfma_f32_16x16x32_bf16 v[76:79], v[162:165], v[218:221], v[76:79]
	v_mfma_f32_16x16x32_bf16 v[72:75], v[170:173], v[218:221], v[72:75]
	v_mfma_f32_16x16x32_bf16 v[124:127], v[166:169], v[198:201], v[124:127]
	v_mfma_f32_16x16x32_bf16 v[120:123], v[174:177], v[198:201], v[120:123]
	v_mfma_f32_16x16x32_bf16 v[108:111], v[166:169], v[206:209], v[108:111]
	v_mfma_f32_16x16x32_bf16 v[104:107], v[174:177], v[206:209], v[104:107]
	v_mfma_f32_16x16x32_bf16 v[92:95], v[166:169], v[214:217], v[92:95]
	v_mfma_f32_16x16x32_bf16 v[88:91], v[174:177], v[214:217], v[88:91]
	v_mfma_f32_16x16x32_bf16 v[76:79], v[166:169], v[222:225], v[76:79]
	v_mfma_f32_16x16x32_bf16 v[72:75], v[174:177], v[222:225], v[72:75]
	s_setprio 0
	s_setprio 1
	v_mfma_f32_16x16x32_bf16 v[116:119], v[178:181], v[194:197], v[116:119]
	v_mfma_f32_16x16x32_bf16 v[112:115], v[186:189], v[194:197], v[112:115]
	v_mfma_f32_16x16x32_bf16 v[100:103], v[178:181], v[202:205], v[100:103]
	v_mfma_f32_16x16x32_bf16 v[96:99], v[186:189], v[202:205], v[96:99]
	v_mfma_f32_16x16x32_bf16 v[84:87], v[178:181], v[210:213], v[84:87]
	v_mfma_f32_16x16x32_bf16 v[80:83], v[186:189], v[210:213], v[80:83]
	v_mfma_f32_16x16x32_bf16 v[68:71], v[178:181], v[218:221], v[68:71]
	v_mfma_f32_16x16x32_bf16 v[64:67], v[186:189], v[218:221], v[64:67]
	v_mfma_f32_16x16x32_bf16 v[116:119], v[182:185], v[198:201], v[116:119]
	v_mfma_f32_16x16x32_bf16 v[112:115], v[190:193], v[198:201], v[112:115]
	v_mfma_f32_16x16x32_bf16 v[100:103], v[182:185], v[206:209], v[100:103]
	v_mfma_f32_16x16x32_bf16 v[96:99], v[190:193], v[206:209], v[96:99]
	v_mfma_f32_16x16x32_bf16 v[84:87], v[182:185], v[214:217], v[84:87]
	v_mfma_f32_16x16x32_bf16 v[80:83], v[190:193], v[214:217], v[80:83]
	v_mfma_f32_16x16x32_bf16 v[68:71], v[182:185], v[222:225], v[68:71]
	v_mfma_f32_16x16x32_bf16 v[64:67], v[190:193], v[222:225], v[64:67]
	s_setprio 0
	s_barrier
	s_add_i32 s52, s69, s15
	v_lshl_add_u64 v[146:147], v[146:147], 0, s[22:23]
	s_mov_b32 m0, s52
	ds_read_b128 v[194:197], v161 offset:49152
	ds_read_b128 v[198:201], v161 offset:50176
	ds_read_b128 v[202:205], v161 offset:51200
	ds_read_b128 v[206:209], v161 offset:52224
	ds_read_b128 v[210:213], v161 offset:53248
	ds_read_b128 v[214:217], v161 offset:54272
	ds_read_b128 v[218:221], v161 offset:55296
	ds_read_b128 v[222:225], v161 offset:56320
	global_load_lds_dwordx4 v[146:147], off
	s_add_i32 m0, s52, 0x2000
	s_add_u32 s52, s56, 0xb0080
	v_lshl_add_u64 v[146:147], v[226:227], 0, s[22:23]
	s_addc_u32 s53, s57, 0
	s_add_i32 s56, s70, s15
	global_load_lds_dwordx4 v[146:147], off
	v_lshl_add_u64 v[146:147], s[52:53], 0, v[132:133]
	s_mov_b32 m0, s56
	s_nop 0
	global_load_lds_dwordx4 v[146:147], off
	v_lshl_add_u64 v[146:147], s[52:53], 0, v[136:137]
	s_add_i32 m0, s56, 0x2000
	s_nop 0
	global_load_lds_dwordx4 v[146:147], off
	v_lshl_add_u64 v[146:147], v[228:229], 0, s[22:23]
	s_mov_b32 m0, s46
	s_nop 0
	global_load_lds_dwordx4 v[146:147], off
	v_lshl_add_u64 v[146:147], v[230:231], 0, s[22:23]
	s_mov_b32 m0, s47
	s_nop 0
	global_load_lds_dwordx4 v[146:147], off
	s_waitcnt vmcnt(10)
	s_waitcnt lgkmcnt(0)
	s_barrier
	s_setprio 1
	s_waitcnt lgkmcnt(0)
	v_mfma_f32_16x16x32_bf16 v[60:63], v[162:165], v[194:197], v[60:63]
	v_mfma_f32_16x16x32_bf16 v[56:59], v[170:173], v[194:197], v[56:59]
	v_mfma_f32_16x16x32_bf16 v[44:47], v[162:165], v[202:205], v[44:47]
	v_mfma_f32_16x16x32_bf16 v[40:43], v[170:173], v[202:205], v[40:43]
	v_mfma_f32_16x16x32_bf16 v[28:31], v[162:165], v[210:213], v[28:31]
	v_mfma_f32_16x16x32_bf16 v[24:27], v[170:173], v[210:213], v[24:27]
	v_mfma_f32_16x16x32_bf16 v[12:15], v[162:165], v[218:221], v[12:15]
	v_mfma_f32_16x16x32_bf16 v[8:11], v[170:173], v[218:221], v[8:11]
	v_mfma_f32_16x16x32_bf16 v[60:63], v[166:169], v[198:201], v[60:63]
	v_mfma_f32_16x16x32_bf16 v[56:59], v[174:177], v[198:201], v[56:59]
	v_mfma_f32_16x16x32_bf16 v[44:47], v[166:169], v[206:209], v[44:47]
	v_mfma_f32_16x16x32_bf16 v[40:43], v[174:177], v[206:209], v[40:43]
	v_mfma_f32_16x16x32_bf16 v[28:31], v[166:169], v[214:217], v[28:31]
	v_mfma_f32_16x16x32_bf16 v[24:27], v[174:177], v[214:217], v[24:27]
	v_mfma_f32_16x16x32_bf16 v[12:15], v[166:169], v[222:225], v[12:15]
	v_mfma_f32_16x16x32_bf16 v[8:11], v[174:177], v[222:225], v[8:11]
	s_setprio 0
	s_setprio 1
	v_mfma_f32_16x16x32_bf16 v[52:55], v[178:181], v[194:197], v[52:55]
	v_mfma_f32_16x16x32_bf16 v[48:51], v[186:189], v[194:197], v[48:51]
	v_mfma_f32_16x16x32_bf16 v[36:39], v[178:181], v[202:205], v[36:39]
	v_mfma_f32_16x16x32_bf16 v[32:35], v[186:189], v[202:205], v[32:35]
	v_mfma_f32_16x16x32_bf16 v[20:23], v[178:181], v[210:213], v[20:23]
	v_mfma_f32_16x16x32_bf16 v[16:19], v[186:189], v[210:213], v[16:19]
	v_mfma_f32_16x16x32_bf16 v[4:7], v[178:181], v[218:221], v[4:7]
	v_mfma_f32_16x16x32_bf16 v[0:3], v[186:189], v[218:221], v[0:3]
	v_mfma_f32_16x16x32_bf16 v[52:55], v[182:185], v[198:201], v[52:55]
	v_mfma_f32_16x16x32_bf16 v[48:51], v[190:193], v[198:201], v[48:51]
	v_mfma_f32_16x16x32_bf16 v[36:39], v[182:185], v[206:209], v[36:39]
	v_mfma_f32_16x16x32_bf16 v[32:35], v[190:193], v[206:209], v[32:35]
	v_mfma_f32_16x16x32_bf16 v[20:23], v[182:185], v[214:217], v[20:23]
	v_mfma_f32_16x16x32_bf16 v[16:19], v[190:193], v[214:217], v[16:19]
	v_mfma_f32_16x16x32_bf16 v[4:7], v[182:185], v[222:225], v[4:7]
	v_mfma_f32_16x16x32_bf16 v[0:3], v[190:193], v[222:225], v[0:3]
	s_setprio 0
	s_barrier
	s_sub_u32 s76, s76, 1
	s_cmp_eq_u32 s76, 0
	s_cselect_b32 s100, 0x70000000, s100
	s_mov_b32 s101, s100
	s_add_i32 s32, s32, 1
	s_cmp_eq_u32 s32, 12
	s_cselect_b32 vcc_lo, 0x3000, 0
	s_cselect_b32 s32, 0, s32
	s_add_u32 s100, s100, vcc_lo
	s_addk_i32 s100, 0x400
	s_add_u32 s37, s37, 0x100
	s_addc_u32 s42, s42, 0
	s_cmp_ge_u32 s68, s33
	s_mov_b64 s[52:53], s[54:55]
	s_mov_b32 s56, s68
	s_cbranch_scc0 .LBB0_1735
	s_xor_b64 s[50:51], s[50:51], -1
	s_and_b64 vcc, exec, s[24:25]
	s_cbranch_vccz .LBB0_1757
